# v020 + mix: second workgroup barrier skipped when the unit's row panel was already acquired
# baseline (speedup 1.0000x reference)
; __device__ __forceinline__ void mix_phase(const Params& p, LAS unsigned char* lds, int G, bool dry) {
;     ...
;         if (!((seen >> (nb >> 1)) & 1ull)) {
;             if (tid < 64) pg8::panel_wait_wave0(pcnt, nb >> 1, 48u);
;             seen |= 1ull << (nb >> 1);
;         }
;         __syncthreads();
;         int nticket = 0;
;         if (tid == 0) nticket = (int)atomicAdd(ctr, 1u);
.LBB0_171:
	s_or_b64 exec, exec, s[30:31]
	s_or_b64 s[28:29], s[10:11], s[28:29]
.LBB0_172:
	s_barrier
.Lmix_seen:
	v_mov_b32_e32 v130, 0
	s_and_saveexec_b64 s[10:11], s[12:13]
	s_cbranch_execz .LBB0_176
	s_mov_b64 s[34:35], exec
	v_mbcnt_lo_u32_b32 v0, s34, 0
	v_mbcnt_hi_u32_b32 v0, s35, v0
	v_cmp_eq_u32_e32 vcc, 0, v0
	s_and_saveexec_b64 s[30:31], vcc
	s_cbranch_execz .LBB0_175
	s_bcnt1_i32_b64 s34, s[34:35]
	v_mov_b32_e32 v1, s34
	global_atomic_add v235, v83, v1, s[86:87] offset:8 sc0
